# FoX unit queues: 4 queues of 16 (b,h) (one batch, all 16 heads, shared by an XCD pair) instead of 8 queues of 8
# baseline (speedup 1.0000x reference)
.Lq_init:
	s_add_u32 s90, s54, 0x80000
	s_addc_u32 s91, s55, 0
	s_getreg_b32 s92, hwreg(HW_REG_XCC_ID, 0, 4)
	s_and_b32 s92, s92, 7
	s_lshr_b32 s92, s92, 1

.Lq_scan:
	s_mov_b64 exec, 0xf
	v_mbcnt_lo_u32_b32 v251, -1, 0
	v_lshlrev_b32_e32 v251, 6, v251
	global_load_dword v250, v251, s[90:91] sc1
	s_waitcnt vmcnt(0)
	v_cmp_gt_u32_e32 vcc, 0x100, v250
	s_mov_b32 s95, vcc_lo
	s_cmp_eq_u32 s95, 0
	s_cbranch_scc1 .Lq_none
	s_lshr_b32 s94, s95, s92
	s_lshl_b32 s94, s94, s92
	s_cmp_lg_u32 s94, 0
	s_cselect_b32 s95, s94, s95
	s_ff1_i32_b32 s92, s95
	s_mov_b64 exec, 1
	v_mov_b32_e32 v250, 1
	s_lshl_b32 s95, s92, 6
	v_mov_b32_e32 v251, s95
	global_atomic_add v250, v251, v250, s[90:91] sc0
	s_waitcnt vmcnt(0)
	v_readfirstlane_b32 s95, v250
	s_cmp_ge_u32 s95, 0x100
	s_cbranch_scc1 .Lq_scan
	s_lshl_b32 s94, s92, 8
	s_or_b32 s95, s95, s94
	s_branch .Lq_pub

.Lq_read:
	v_mov_b32_e32 v252, 0x1c000
	ds_read_b32 v250, v252
	s_waitcnt lgkmcnt(0)
	v_readfirstlane_b32 s95, v250
	s_barrier
	s_bitcmp1_b32 s95, 30
	s_cbranch_scc1 .Lq_fetch
	s_bitcmp1_b32 s95, 31
	s_cbranch_scc1 .LBB0_662
	s_lshr_b32 s92, s95, 8
	s_and_b32 s95, s95, 0xff
	s_lshr_b32 s94, s95, 4
	s_sub_i32 s94, 15, s94
	s_and_b32 s88, s95, 15
	s_lshl_b32 s96, s92, 4
	s_or_b32 s88, s88, s96
	s_lshl_b32 s88, s88, 3

.Lq_fill_done:
.LBB0_646:
	v_mul_lo_u32 v157, v146, s45
	v_lshlrev_b32_e32 v158, 4, v0
	v_add3_u32 v0, 0, v157, v158
	s_waitcnt vmcnt(0)
	v_readfirstlane_b32 s96, v255
	s_cmp_lg_u32 s96, 0
	s_cbranch_scc1 .Lq_w1
	s_mov_b64 s[96:97], exec
	s_mov_b64 exec, 1
	s_lshl_b32 s95, s92, 8
	v_or_b32_e32 v251, s95, v250
	v_mov_b32_e32 v253, 0x40000000
	v_cmp_gt_u32_e32 vcc, 0x100, v250
	v_mov_b32_e32 v252, 0x1c000
	v_cndmask_b32_e32 v251, v253, v251, vcc
	ds_write_b32 v252, v251
	s_mov_b64 exec, s[96:97]
